# v50 + attention MODE-1 epilogue: 16 IEEE 1/sqrtf chains of the headwise rmsnorm replaced by v_rsq_f32 (early, via spare VGPRs), leftover hazard nops removed
# speedup vs baseline: 1.0143x; 1.0143x over previous
.LBB0_749:
	s_or_b64 exec, exec, s[4:5]
	s_waitcnt lgkmcnt(0)
	ds_read_b128 v[68:71], v66 offset:128
	ds_read_b128 v[72:75], v66 offset:160
	s_mov_b64 s[6:7], s[0:1]
	s_add_u32 s4, s10, s13
	s_addc_u32 s5, s37, s14
	s_waitcnt lgkmcnt(1)
	v_rcp_f32_e32 v67, v68
	v_rcp_f32_e32 v76, v69
	v_rcp_f32_e32 v77, v70
	v_rcp_f32_e32 v78, v71
	s_waitcnt lgkmcnt(0)
	v_rcp_f32_e32 v79, v72
	ds_read_b128 v[68:71], v66 offset:192
	v_rcp_f32_e32 v80, v73
	v_rcp_f32_e32 v81, v74
	v_rcp_f32_e32 v82, v75
	ds_read_b128 v[72:75], v66 offset:224
	s_load_dwordx2 s[6:7], s[6:7], 0xa0
	s_lshl_b64 s[4:5], s[4:5], 11
	s_waitcnt lgkmcnt(0)
	v_rcp_f32_e32 v66, v68
	v_rcp_f32_e32 v68, v69
	v_rcp_f32_e32 v69, v70
	s_add_u32 s8, s6, s4
	v_rcp_f32_e32 v70, v71
	v_rcp_f32_e32 v71, v72
	v_rcp_f32_e32 v72, v73
	v_rcp_f32_e32 v73, v74
	v_rcp_f32_e32 v74, v75
	s_addc_u32 s9, s7, s5
	s_lshl_b32 s4, s12, 12
	s_add_i32 s10, s4, 0
	v_mul_f32_e32 v18, v18, v67
	v_mul_f32_e32 v50, v50, v67
	v_mul_f32_e32 v34, v34, v67
	v_mul_f32_e32 v67, v2, v67
	s_add_i32 s10, s10, 0x16800
	v_lshlrev_b32_e32 v2, 4, v1
	v_mul_f32_e32 v75, v3, v76
	s_mov_b64 s[4:5], s[0:1]
	v_and_b32_e32 v3, 0x380, v2
	v_add_u32_e32 v2, s10, v188
	v_mul_f32_e32 v89, v48, v73
	v_mul_f32_e32 v48, v65, v74
	v_add_u32_e32 v65, v2, v3
	v_mul_f32_e32 v19, v19, v76
	v_mul_f32_e32 v51, v51, v76
	v_mul_f32_e32 v35, v35, v76
	v_mul_f32_e32 v76, v4, v77
	s_load_dwordx2 s[4:5], s[4:5], 0x70
	v_lshlrev_b32_e32 v3, 1, v207
	v_lshlrev_b32_e32 v4, 9, v208
	s_waitcnt vmcnt(5)
	ds_write_b128 v65, v[138:141]
	ds_write_b128 v65, v[130:133] offset:1024
	ds_write_b128 v65, v[134:137] offset:2048
	s_waitcnt vmcnt(3)
	ds_write_b128 v65, v[142:145] offset:3072
	v_mul_f32_e32 v85, v10, v66
	v_mul_f32_e32 v10, v27, v68
	v_mul_f32_e32 v27, v59, v68
	v_mul_f32_e32 v59, v60, v69
	v_mul_f32_e32 v60, v12, v69
	v_mul_f32_e32 v12, v29, v70
	v_mul_f32_e32 v29, v61, v70
	v_mul_f32_e32 v30, v30, v71
	v_mul_f32_e32 v61, v62, v71
	v_mul_f32_e32 v86, v46, v71
	v_mul_f32_e32 v87, v14, v71
	v_add3_u32 v71, s10, v3, v4
	s_waitcnt lgkmcnt(0)
	v_mul_f32_e32 v20, v20, v77
	v_mul_f32_e32 v52, v52, v77
	v_mul_f32_e32 v36, v36, v77
	v_mul_f32_e32 v21, v21, v78
	v_mul_f32_e32 v53, v53, v78
	v_mul_f32_e32 v77, v37, v78
	v_mul_f32_e32 v78, v5, v78
	v_mul_f32_e32 v5, v22, v79
	v_mul_f32_e32 v22, v54, v79
	v_mul_f32_e32 v38, v38, v79
	v_mul_f32_e32 v79, v6, v79
	v_mul_f32_e32 v6, v23, v80
	v_mul_f32_e32 v23, v55, v80
	v_mul_f32_e32 v83, v39, v80
	v_mul_f32_e32 v80, v7, v80
	v_mul_f32_e32 v7, v24, v81
	v_mul_f32_e32 v24, v56, v81
	v_mul_f32_e32 v84, v40, v81
	v_mul_f32_e32 v81, v8, v81
	v_mul_f32_e32 v8, v25, v82
	v_mul_f32_e32 v25, v57, v82
	v_mul_f32_e32 v41, v41, v82
	v_mul_f32_e32 v57, v9, v82
	v_mul_f32_e32 v9, v26, v66
	v_mul_f32_e32 v26, v58, v66
	v_mul_f32_e32 v82, v42, v66
	v_mul_f32_e32 v28, v28, v69
	v_mul_f32_e32 v44, v44, v69
	v_mul_f32_e32 v66, v31, v72
	v_mul_f32_e32 v69, v32, v73
	v_mul_f32_e32 v90, v16, v73
	v_mul_f32_e32 v16, v33, v74
	ds_read_u16 v14, v71
	ds_read_u16 v31, v71 offset:64
	ds_read_u16 v32, v71 offset:128
	ds_read_u16 v33, v71 offset:192
	ds_read_u16 v37, v71 offset:256
	ds_read_u16 v39, v71 offset:320
	ds_read_u16 v40, v71 offset:384
	ds_read_u16 v42, v71 offset:448
	s_waitcnt lgkmcnt(0)
	v_lshlrev_b32_e32 v14, 16, v14
	v_fma_f32 v92, -v203, v18, v14
	v_lshlrev_b32_e32 v14, 16, v31
	v_fma_f32 v93, -v203, v50, v14
	v_lshlrev_b32_e32 v14, 16, v32
	v_fma_f32 v94, -v203, v19, v14
	v_lshlrev_b32_e32 v14, 16, v33
	v_fma_f32 v51, -v203, v51, v14
	v_lshlrev_b32_e32 v14, 16, v37
	v_fma_f32 v37, -v203, v20, v14
	v_lshlrev_b32_e32 v14, 16, v39
	v_fma_f32 v32, -v203, v52, v14
	v_lshlrev_b32_e32 v14, 16, v40
	v_fma_f32 v46, -v203, v21, v14
	v_lshlrev_b32_e32 v14, 16, v42
	v_fma_f32 v40, -v203, v53, v14
	ds_read_u16 v14, v71 offset:1024
	ds_read_u16 v18, v71 offset:1088
	ds_read_u16 v19, v71 offset:1152
	ds_read_u16 v20, v71 offset:1216
	ds_read_u16 v21, v71 offset:1280
	ds_read_u16 v31, v71 offset:1344
	ds_read_u16 v33, v71 offset:1408
	ds_read_u16 v39, v71 offset:1472
	s_waitcnt lgkmcnt(7)
	v_lshlrev_b32_e32 v14, 16, v14
	v_fma_f32 v55, -v203, v5, v14
	s_waitcnt lgkmcnt(6)
	v_lshlrev_b32_e32 v5, 16, v18
	v_mul_f32_e32 v91, v49, v74
	v_fma_f32 v49, -v203, v22, v5
	s_waitcnt lgkmcnt(5)
	v_lshlrev_b32_e32 v5, 16, v19
	v_mul_f32_e32 v43, v43, v68
	v_mul_f32_e32 v11, v11, v68
	v_mul_f32_e32 v68, v63, v72
	v_fma_f32 v63, -v203, v6, v5
	s_waitcnt lgkmcnt(4)
	v_lshlrev_b32_e32 v5, 16, v20
	v_fma_f32 v58, -v203, v23, v5
	s_waitcnt lgkmcnt(3)
	v_lshlrev_b32_e32 v5, 16, v21
	v_mul_f32_e32 v45, v45, v70
	v_mul_f32_e32 v13, v13, v70
	v_mul_f32_e32 v70, v64, v73
	v_fma_f32 v64, -v203, v7, v5
	s_waitcnt lgkmcnt(2)
	v_lshlrev_b32_e32 v5, 16, v31
	v_fma_f32 v62, -v203, v24, v5
	s_waitcnt lgkmcnt(1)
	v_lshlrev_b32_e32 v5, 16, v33
	v_fma_f32 v56, -v203, v8, v5
	s_waitcnt lgkmcnt(0)
	v_lshlrev_b32_e32 v5, 16, v39
	v_fma_f32 v54, -v203, v25, v5
	ds_read_u16 v5, v71 offset:2048
	ds_read_u16 v6, v71 offset:2112
	ds_read_u16 v7, v71 offset:2176
	ds_read_u16 v8, v71 offset:2240
	ds_read_u16 v14, v71 offset:2304
	ds_read_u16 v18, v71 offset:2368
	ds_read_u16 v19, v71 offset:2432
	ds_read_u16 v20, v71 offset:2496
	s_waitcnt lgkmcnt(7)
	v_lshlrev_b32_e32 v5, 16, v5
	v_fma_f32 v50, -v203, v9, v5
	s_waitcnt lgkmcnt(6)
	v_lshlrev_b32_e32 v5, 16, v6
	v_mul_f32_e32 v88, v47, v72
	v_fma_f32 v47, -v203, v26, v5
	s_waitcnt lgkmcnt(5)
	v_lshlrev_b32_e32 v5, 16, v7
	v_fma_f32 v42, -v203, v10, v5
	s_waitcnt lgkmcnt(4)
	v_lshlrev_b32_e32 v5, 16, v8
	v_fma_f32 v39, -v203, v27, v5
	s_waitcnt lgkmcnt(3)
	v_lshlrev_b32_e32 v5, 16, v14
	v_fma_f32 v33, -v203, v28, v5
	s_waitcnt lgkmcnt(2)
	v_lshlrev_b32_e32 v5, 16, v18
	v_fma_f32 v31, -v203, v59, v5
	s_waitcnt lgkmcnt(1)
	v_lshlrev_b32_e32 v5, 16, v19
	v_fma_f32 v23, -v203, v12, v5
	s_waitcnt lgkmcnt(0)
	v_lshlrev_b32_e32 v5, 16, v20
	v_fma_f32 v21, -v203, v29, v5
	ds_read_u16 v5, v71 offset:3072
	ds_read_u16 v6, v71 offset:3136
	ds_read_u16 v7, v71 offset:3200
	ds_read_u16 v8, v71 offset:3264
	ds_read_u16 v18, v71 offset:3328
	ds_read_u16 v19, v71 offset:3392
	ds_read_u16 v20, v71 offset:3456
	ds_read_u16 v22, v71 offset:3520
	s_waitcnt lgkmcnt(7)
	v_lshlrev_b32_e32 v5, 16, v5
	v_fma_f32 v14, -v203, v30, v5
	s_waitcnt lgkmcnt(6)
	v_lshlrev_b32_e32 v5, 16, v6
	v_fma_f32 v12, -v203, v61, v5
	s_waitcnt lgkmcnt(5)
	v_lshlrev_b32_e32 v5, 16, v7
	v_fma_f32 v9, -v203, v66, v5
	s_waitcnt lgkmcnt(4)
	v_lshlrev_b32_e32 v5, 16, v8
	v_fma_f32 v10, -v203, v68, v5
	s_waitcnt lgkmcnt(3)
	v_lshlrev_b32_e32 v5, 16, v18
	v_fma_f32 v8, -v203, v69, v5
	s_waitcnt lgkmcnt(2)
	v_lshlrev_b32_e32 v5, 16, v19
	s_waitcnt lgkmcnt(0)
	ds_write_b128 v65, v[114:117]
	s_waitcnt vmcnt(2)
	ds_write_b128 v65, v[118:121] offset:1024
	s_waitcnt vmcnt(1)
	ds_write_b128 v65, v[122:125] offset:2048
	s_waitcnt vmcnt(0)
	ds_write_b128 v65, v[126:129] offset:3072
	v_fma_f32 v7, -v203, v70, v5
	s_waitcnt lgkmcnt(5)
	v_lshlrev_b32_e32 v5, 16, v20
	s_waitcnt lgkmcnt(0)
	v_fma_f32 v5, -v203, v16, v5
	s_waitcnt lgkmcnt(4)
	v_lshlrev_b32_e32 v6, 16, v22
	ds_read_u16 v16, v71
	ds_read_u16 v18, v71 offset:64
	ds_read_u16 v19, v71 offset:128
	ds_read_u16 v20, v71 offset:192
	ds_read_u16 v22, v71 offset:256
	ds_read_u16 v24, v71 offset:320
	ds_read_u16 v25, v71 offset:384
	ds_read_u16 v26, v71 offset:448
	s_waitcnt lgkmcnt(7)
	v_lshlrev_b32_e32 v16, 16, v16
	v_fma_f32 v29, -v203, v34, v16
	s_waitcnt lgkmcnt(6)
	v_lshlrev_b32_e32 v16, 16, v18
	v_fma_f32 v52, -v203, v67, v16
	s_waitcnt lgkmcnt(5)
	v_lshlrev_b32_e32 v16, 16, v19
	v_fma_f32 v59, -v203, v35, v16
	s_waitcnt lgkmcnt(4)
	v_lshlrev_b32_e32 v16, 16, v20
	v_fma_f32 v6, -v203, v48, v6
	v_fma_f32 v67, -v203, v75, v16
	ds_read_u16 v16, v71 offset:1024
	ds_read_u16 v18, v71 offset:1088
	ds_read_u16 v19, v71 offset:1152
	ds_read_u16 v20, v71 offset:1216
	ds_read_u16 v27, v71 offset:1280
	ds_read_u16 v28, v71 offset:1344
	ds_read_u16 v30, v71 offset:1408
	ds_read_u16 v34, v71 offset:1472
	ds_read_u16 v35, v71 offset:2048
	ds_read_u16 v48, v71 offset:2112
	ds_read_u16 v53, v71 offset:2176
	ds_read_u16 v75, v71 offset:2240
	ds_read_u16 v95, v71 offset:2304
	ds_read_u16 v96, v71 offset:2368
	ds_read_u16 v97, v71 offset:2432
	ds_read_u16 v98, v71 offset:2496
	ds_read_u16 v99, v71 offset:3072
	ds_read_u16 v100, v71 offset:3136
	ds_read_u16 v101, v71 offset:3200
	ds_read_u16 v102, v71 offset:3264
	ds_read_u16 v103, v71 offset:3328
	ds_read_u16 v104, v71 offset:3392
	ds_read_u16 v105, v71 offset:3456
	ds_read_u16 v106, v71 offset:3520
	s_waitcnt lgkmcnt(14)
	v_lshlrev_b32_e32 v22, 16, v22
	v_fma_f32 v109, -v203, v36, v22
	v_lshlrev_b32_e32 v22, 16, v24
	v_lshlrev_b32_e32 v16, 16, v16
	v_fma_f32 v76, -v203, v76, v22
	v_lshlrev_b32_e32 v22, 16, v25
	v_fma_f32 v110, -v203, v38, v16
	v_lshlrev_b32_e32 v16, 16, v18
	s_waitcnt lgkmcnt(0)
	v_lshlrev_b32_e32 v61, 2, v207
	v_fma_f32 v77, -v203, v77, v22
	v_lshlrev_b32_e32 v22, 16, v26
	v_fma_f32 v66, -v203, v79, v16
	v_lshlrev_b32_e32 v16, 16, v19
	global_load_dword v107, v61, s[4:5]
	global_load_dword v108, v61, s[4:5] offset:128
	v_fma_f32 v78, -v203, v78, v22
	v_fma_f32 v71, -v203, v83, v16
	v_lshlrev_b32_e32 v16, 16, v20
	global_load_dword v20, v61, s[4:5] offset:256
	global_load_dword v22, v61, s[4:5] offset:384
	v_fma_f32 v70, -v203, v80, v16
	v_lshlrev_b32_e32 v16, 16, v27
	v_mul_f32_e32 v17, v17, v74
	v_fma_f32 v74, -v203, v84, v16
	v_lshlrev_b32_e32 v16, 16, v28
	v_fma_f32 v73, -v203, v81, v16
	v_lshlrev_b32_e32 v16, 16, v30
	v_mul_f32_e32 v15, v15, v72
	v_fma_f32 v72, -v203, v41, v16
	v_lshlrev_b32_e32 v16, 16, v34
	v_fma_f32 v69, -v203, v57, v16
	v_lshlrev_b32_e32 v16, 16, v35
	v_fma_f32 v68, -v203, v82, v16
	v_lshlrev_b32_e32 v16, 16, v48
	v_fma_f32 v65, -v203, v85, v16
	s_waitcnt lgkmcnt(13)
	v_lshlrev_b32_e32 v16, 16, v53
	v_fma_f32 v61, -v203, v43, v16
	s_waitcnt lgkmcnt(12)
	v_lshlrev_b32_e32 v16, 16, v75
	v_fma_f32 v57, -v203, v11, v16
	v_mul_f32_e32 v16, v93, v93
	v_mul_f32_e32 v18, v52, v52
	v_fmac_f32_e32 v16, v92, v92
	v_fmac_f32_e32 v18, v29, v29
	v_add_f32_e32 v16, v16, v18
	ds_bpermute_b32 v18, v198, v16
	s_waitcnt lgkmcnt(12)
	v_lshlrev_b32_e32 v11, 16, v95
	v_fma_f32 v53, -v203, v44, v11
	s_waitcnt lgkmcnt(11)
	v_lshlrev_b32_e32 v11, 16, v96
	v_fma_f32 v48, -v203, v60, v11
	s_waitcnt lgkmcnt(0)
	v_add_f32_e32 v16, v16, v18
	ds_bpermute_b32 v18, v199, v16
	v_lshlrev_b32_e32 v11, 16, v97
	v_fma_f32 v45, -v203, v45, v11
	v_lshlrev_b32_e32 v11, 16, v98
	v_fma_f32 v41, -v203, v13, v11
	s_waitcnt lgkmcnt(0)
	v_add_f32_e32 v13, v16, v18
	ds_bpermute_b32 v16, v200, v13
	v_lshlrev_b32_e32 v11, 16, v99
	v_fma_f32 v38, -v203, v86, v11
	v_lshlrev_b32_e32 v11, 16, v100
	v_fma_f32 v34, -v203, v87, v11
	s_waitcnt lgkmcnt(0)
	v_add_f32_e32 v13, v13, v16
	ds_bpermute_b32 v18, v201, v13
	v_lshlrev_b32_e32 v11, 16, v101
	v_fma_f32 v30, -v203, v88, v11
	v_lshlrev_b32_e32 v11, 16, v102
	v_fma_f32 v24, -v203, v15, v11
	s_waitcnt lgkmcnt(0)
	v_add_f32_e32 v15, v13, v18
	ds_bpermute_b32 v18, v196, v15
	v_lshlrev_b32_e32 v11, 16, v103
	v_fma_f32 v16, -v203, v89, v11
	v_lshlrev_b32_e32 v11, 16, v104
	v_fma_f32 v19, -v203, v90, v11
	s_waitcnt lgkmcnt(0)
	v_add_f32_e32 v15, v15, v18
	v_fmamk_f32 v15, v15, 0x3c000000, v204
	v_rsq_f32_e32 v224, v15
	v_lshlrev_b32_e32 v11, 16, v105
	v_fma_f32 v13, -v203, v91, v11
	v_lshlrev_b32_e32 v11, 16, v106
	v_fma_f32 v15, -v203, v17, v11
	v_lshrrev_b32_e32 v1, 3, v1
	v_mov_b32_e32 v189, v146
	s_waitcnt vmcnt(3)
	v_mul_f32_e32 v18, 0x3f24fd5c, v107
	v_mul_f32_e32 v26, v51, v51
	v_mul_f32_e32 v27, v67, v67
	v_fmac_f32_e32 v26, v94, v94
	v_fmac_f32_e32 v27, v59, v59
	v_add_f32_e32 v26, v26, v27
	ds_bpermute_b32 v27, v198, v26
	s_waitcnt vmcnt(2)
	v_mul_f32_e32 v17, 0x3f24fd5c, v108
	s_waitcnt lgkmcnt(0)
	v_add_f32_e32 v27, v26, v27
	ds_bpermute_b32 v36, v199, v27
	s_waitcnt vmcnt(1)
	v_mul_f32_e32 v26, 0x3f24fd5c, v20
	s_waitcnt vmcnt(0)
	v_mul_f32_e32 v25, 0x3f24fd5c, v22
	s_waitcnt lgkmcnt(0)
	v_add_f32_e32 v20, v27, v36
	ds_bpermute_b32 v22, v200, v20
	s_waitcnt lgkmcnt(0)
	v_add_f32_e32 v20, v20, v22
	ds_bpermute_b32 v22, v201, v20
	v_mov_b32_e32 v35, v224
	s_waitcnt lgkmcnt(0)
	v_add_f32_e32 v20, v20, v22
	ds_bpermute_b32 v22, v196, v20
	v_mul_f32_e32 v11, v18, v35
	v_mul_f32_e32 v27, v92, v11
	v_mul_f32_e32 v11, v17, v35
	v_mul_f32_e32 v28, v93, v11
	s_waitcnt lgkmcnt(0)
	v_add_f32_e32 v20, v20, v22
	v_fmamk_f32 v20, v20, 0x3c000000, v204
	v_rsq_f32_e32 v225, v20
	v_mul_f32_e32 v11, v26, v35
	v_mul_f32_e32 v11, v29, v11
	v_mul_f32_e32 v29, v32, v32
	v_mul_f32_e32 v36, v76, v76
	v_fmac_f32_e32 v29, v37, v37
	v_fmac_f32_e32 v36, v109, v109
	v_add_f32_e32 v29, v29, v36
	ds_bpermute_b32 v36, v198, v29
	s_waitcnt lgkmcnt(0)
	v_add_f32_e32 v29, v29, v36
	ds_bpermute_b32 v36, v199, v29
	v_mul_f32_e32 v20, v25, v35
	v_mul_f32_e32 v20, v52, v20
	s_waitcnt lgkmcnt(0)
	v_add_f32_e32 v29, v29, v36
	ds_bpermute_b32 v35, v200, v29
	s_waitcnt lgkmcnt(0)
	v_add_f32_e32 v29, v29, v35
	ds_bpermute_b32 v35, v201, v29
	v_mov_b32_e32 v44, v225
	s_waitcnt lgkmcnt(0)
	v_add_f32_e32 v29, v29, v35
	ds_bpermute_b32 v43, v196, v29
	v_mul_f32_e32 v22, v18, v44
	v_mul_f32_e32 v35, v94, v22
	v_mul_f32_e32 v22, v17, v44
	s_waitcnt lgkmcnt(0)
	v_add_f32_e32 v29, v29, v43
	v_fmamk_f32 v29, v29, 0x3c000000, v204
	v_rsq_f32_e32 v226, v29
	v_mul_f32_e32 v36, v51, v22
	v_mul_f32_e32 v22, v26, v44
	v_mul_f32_e32 v22, v59, v22
	v_mul_f32_e32 v51, v40, v40
	v_mul_f32_e32 v52, v78, v78
	v_fmac_f32_e32 v51, v46, v46
	v_fmac_f32_e32 v52, v77, v77
	v_add_f32_e32 v51, v51, v52
	ds_bpermute_b32 v52, v198, v51
	s_waitcnt lgkmcnt(0)
	v_add_f32_e32 v51, v51, v52
	ds_bpermute_b32 v52, v199, v51
	v_mul_f32_e32 v29, v25, v44
	v_mul_f32_e32 v29, v67, v29
	s_waitcnt lgkmcnt(0)
	v_add_f32_e32 v44, v51, v52
	ds_bpermute_b32 v51, v200, v44
	s_waitcnt lgkmcnt(0)
	v_add_f32_e32 v44, v44, v51
	ds_bpermute_b32 v51, v201, v44
	v_mov_b32_e32 v52, v226
	s_waitcnt lgkmcnt(0)
	v_add_f32_e32 v44, v44, v51
	ds_bpermute_b32 v51, v196, v44
	v_mul_f32_e32 v43, v18, v52
	v_mul_f32_e32 v43, v37, v43
	v_mul_f32_e32 v37, v17, v52
	s_waitcnt lgkmcnt(0)
	v_add_f32_e32 v44, v44, v51
	v_fmamk_f32 v44, v44, 0x3c000000, v204
	v_rsq_f32_e32 v227, v44
	v_mul_f32_e32 v44, v32, v37
	v_mul_f32_e32 v32, v26, v52
	v_mul_f32_e32 v32, v109, v32
	v_mul_f32_e32 v59, v49, v49
	v_mul_f32_e32 v60, v66, v66
	v_fmac_f32_e32 v59, v55, v55
	v_fmac_f32_e32 v60, v110, v110
	v_add_f32_e32 v59, v59, v60
	ds_bpermute_b32 v60, v198, v59
	s_waitcnt lgkmcnt(0)
	v_add_f32_e32 v59, v59, v60
	ds_bpermute_b32 v60, v199, v59
	v_mul_f32_e32 v37, v25, v52
	v_mul_f32_e32 v37, v76, v37
	s_waitcnt lgkmcnt(0)
	v_add_f32_e32 v52, v59, v60
	ds_bpermute_b32 v59, v200, v52
	s_waitcnt lgkmcnt(0)
	v_add_f32_e32 v52, v52, v59
	ds_bpermute_b32 v59, v201, v52
	v_mov_b32_e32 v60, v227
	s_waitcnt lgkmcnt(0)
	v_add_f32_e32 v52, v52, v59
	ds_bpermute_b32 v59, v196, v52
	v_mul_f32_e32 v51, v18, v60
	v_mul_f32_e32 v51, v46, v51
	v_mul_f32_e32 v46, v17, v60
	s_waitcnt lgkmcnt(0)
	v_add_f32_e32 v52, v52, v59
	v_fmamk_f32 v52, v52, 0x3c000000, v204
	v_rsq_f32_e32 v228, v52
	v_mul_f32_e32 v52, v40, v46
	v_mul_f32_e32 v40, v26, v60
	v_mul_f32_e32 v40, v77, v40
	v_mul_f32_e32 v67, v58, v58
	v_mul_f32_e32 v75, v70, v70
	v_fmac_f32_e32 v67, v63, v63
	v_fmac_f32_e32 v75, v71, v71
	v_add_f32_e32 v67, v67, v75
	ds_bpermute_b32 v75, v198, v67
	s_waitcnt lgkmcnt(0)
	v_add_f32_e32 v67, v67, v75
	ds_bpermute_b32 v75, v199, v67
	v_mul_f32_e32 v46, v25, v60
	v_mul_f32_e32 v46, v78, v46
	s_waitcnt lgkmcnt(0)
	v_add_f32_e32 v60, v67, v75
	ds_bpermute_b32 v67, v200, v60
	s_waitcnt lgkmcnt(0)
	v_add_f32_e32 v60, v60, v67
	ds_bpermute_b32 v67, v201, v60
	v_mov_b32_e32 v75, v228
	s_waitcnt lgkmcnt(0)
	v_add_f32_e32 v60, v60, v67
	ds_bpermute_b32 v67, v196, v60
	v_mul_f32_e32 v59, v18, v75
	v_mul_f32_e32 v59, v55, v59
	v_mul_f32_e32 v55, v17, v75
	s_waitcnt lgkmcnt(0)
	v_add_f32_e32 v60, v60, v67
	v_fmamk_f32 v60, v60, 0x3c000000, v204
	v_rsq_f32_e32 v229, v60
	v_mul_f32_e32 v60, v49, v55
	v_mul_f32_e32 v49, v26, v75
	v_mul_f32_e32 v49, v110, v49
	v_mul_f32_e32 v76, v62, v62
	v_mul_f32_e32 v77, v73, v73
	v_fmac_f32_e32 v76, v64, v64
	v_fmac_f32_e32 v77, v74, v74
	v_add_f32_e32 v76, v76, v77
	ds_bpermute_b32 v77, v198, v76
	s_waitcnt lgkmcnt(0)
	v_add_f32_e32 v76, v76, v77
	ds_bpermute_b32 v77, v199, v76
	v_mul_f32_e32 v55, v25, v75
	v_mul_f32_e32 v55, v66, v55
	s_waitcnt lgkmcnt(0)
	v_add_f32_e32 v66, v76, v77
	ds_bpermute_b32 v75, v200, v66
	s_waitcnt lgkmcnt(0)
	v_add_f32_e32 v66, v66, v75
	ds_bpermute_b32 v75, v201, v66
	v_mov_b32_e32 v76, v229
	s_waitcnt lgkmcnt(0)
	v_add_f32_e32 v75, v66, v75
	ds_bpermute_b32 v77, v196, v75
	v_mul_f32_e32 v66, v18, v76
	v_mul_f32_e32 v66, v63, v66
	v_mul_f32_e32 v63, v17, v76
	s_waitcnt lgkmcnt(0)
	v_add_f32_e32 v67, v75, v77
	v_fmamk_f32 v67, v67, 0x3c000000, v204
	v_rsq_f32_e32 v230, v67
	v_mul_f32_e32 v67, v58, v63
	v_mul_f32_e32 v58, v26, v76
	v_mul_f32_e32 v58, v71, v58
	v_mul_f32_e32 v77, v69, v69
	v_fmac_f32_e32 v77, v72, v72
	v_mul_f32_e32 v71, v54, v54
	v_fmac_f32_e32 v71, v56, v56
	v_add_f32_e32 v71, v71, v77
	ds_bpermute_b32 v77, v198, v71
	s_waitcnt lgkmcnt(0)
	v_add_f32_e32 v71, v71, v77
	ds_bpermute_b32 v77, v199, v71
	v_mul_f32_e32 v63, v25, v76
	v_mul_f32_e32 v63, v70, v63
	s_waitcnt lgkmcnt(0)
	v_add_f32_e32 v70, v71, v77
	ds_bpermute_b32 v71, v200, v70
	s_waitcnt lgkmcnt(0)
	v_add_f32_e32 v70, v70, v71
	ds_bpermute_b32 v71, v201, v70
	v_mov_b32_e32 v75, v230
	s_waitcnt lgkmcnt(0)
	v_add_f32_e32 v71, v70, v71
	ds_bpermute_b32 v77, v196, v71
	v_mul_f32_e32 v70, v18, v75
	v_mul_f32_e32 v70, v64, v70
	v_mul_f32_e32 v64, v17, v75
	s_waitcnt lgkmcnt(0)
	v_add_f32_e32 v71, v71, v77
	v_fmamk_f32 v71, v71, 0x3c000000, v204
	v_rsq_f32_e32 v231, v71
	v_mul_f32_e32 v71, v62, v64
	v_mul_f32_e32 v62, v26, v75
	v_mul_f32_e32 v62, v74, v62
	v_mul_f32_e32 v77, v65, v65
	v_fmac_f32_e32 v77, v68, v68
	v_mul_f32_e32 v74, v47, v47
	v_fmac_f32_e32 v74, v50, v50
	v_add_f32_e32 v74, v74, v77
	ds_bpermute_b32 v77, v198, v74
	s_waitcnt lgkmcnt(0)
	v_add_f32_e32 v74, v74, v77
	ds_bpermute_b32 v77, v199, v74
	v_mul_f32_e32 v64, v25, v75
	v_mul_f32_e32 v64, v73, v64
	s_waitcnt lgkmcnt(0)
	v_add_f32_e32 v73, v74, v77
	ds_bpermute_b32 v74, v200, v73
	s_waitcnt lgkmcnt(0)
	v_add_f32_e32 v73, v73, v74
	ds_bpermute_b32 v74, v201, v73
	v_mov_b32_e32 v75, v231
	s_waitcnt lgkmcnt(0)
	v_add_f32_e32 v74, v73, v74
	ds_bpermute_b32 v77, v196, v74
	v_mul_f32_e32 v73, v18, v75
	v_mul_f32_e32 v73, v56, v73
	v_mul_f32_e32 v56, v17, v75
	s_waitcnt lgkmcnt(0)
	v_add_f32_e32 v74, v74, v77
	v_fmamk_f32 v74, v74, 0x3c000000, v204
	v_rsq_f32_e32 v224, v74
	v_mul_f32_e32 v74, v54, v56
	v_mul_f32_e32 v54, v26, v75
	v_mul_f32_e32 v54, v72, v54
	v_mul_f32_e32 v77, v57, v57
	v_fmac_f32_e32 v77, v61, v61
	v_mul_f32_e32 v72, v39, v39
	v_fmac_f32_e32 v72, v42, v42
	v_add_f32_e32 v72, v72, v77
	ds_bpermute_b32 v77, v198, v72
	s_waitcnt lgkmcnt(0)
	v_add_f32_e32 v72, v72, v77
	ds_bpermute_b32 v77, v199, v72
	v_mul_f32_e32 v56, v25, v75
	v_mul_f32_e32 v56, v69, v56
	s_waitcnt lgkmcnt(0)
	v_add_f32_e32 v69, v72, v77
	ds_bpermute_b32 v72, v200, v69
	s_waitcnt lgkmcnt(0)
	v_add_f32_e32 v69, v69, v72
	ds_bpermute_b32 v72, v201, v69
	v_mov_b32_e32 v75, v224
	s_waitcnt lgkmcnt(0)
	v_add_f32_e32 v72, v69, v72
	ds_bpermute_b32 v77, v196, v72
	v_mul_f32_e32 v69, v18, v75
	v_mul_f32_e32 v69, v50, v69
	v_mul_f32_e32 v50, v17, v75
	s_waitcnt lgkmcnt(0)
	v_add_f32_e32 v72, v72, v77
	v_fmamk_f32 v72, v72, 0x3c000000, v204
	v_rsq_f32_e32 v225, v72
	v_mul_f32_e32 v72, v47, v50
	v_mul_f32_e32 v47, v26, v75
	v_mul_f32_e32 v47, v68, v47
	v_mul_f32_e32 v77, v48, v48
	v_fmac_f32_e32 v77, v53, v53
	v_mul_f32_e32 v68, v31, v31
	v_fmac_f32_e32 v68, v33, v33
	v_add_f32_e32 v68, v68, v77
	ds_bpermute_b32 v77, v198, v68
	s_waitcnt lgkmcnt(0)
	v_add_f32_e32 v68, v68, v77
	ds_bpermute_b32 v77, v199, v68
	v_mul_f32_e32 v50, v25, v75
	v_mul_f32_e32 v50, v65, v50
	s_waitcnt lgkmcnt(0)
	v_add_f32_e32 v65, v68, v77
	ds_bpermute_b32 v68, v200, v65
	s_waitcnt lgkmcnt(0)
	v_add_f32_e32 v65, v65, v68
	ds_bpermute_b32 v68, v201, v65
	v_mov_b32_e32 v75, v225
	s_waitcnt lgkmcnt(0)
	v_add_f32_e32 v65, v65, v68
	ds_bpermute_b32 v68, v196, v65
	v_mul_f32_e32 v76, v18, v75
	v_mul_f32_e32 v76, v42, v76
	v_mul_f32_e32 v42, v17, v75
	v_mul_f32_e32 v77, v39, v42
	s_waitcnt lgkmcnt(0)
	v_add_f32_e32 v65, v65, v68
	v_fmamk_f32 v65, v65, 0x3c000000, v204
	v_mul_f32_e32 v39, v26, v75
	v_mul_f32_e32 v39, v61, v39
	v_mul_f32_e32 v68, v41, v41
	v_fmac_f32_e32 v68, v45, v45
	v_mul_f32_e32 v61, v21, v21
	v_fmac_f32_e32 v61, v23, v23
	v_add_f32_e32 v61, v61, v68
	ds_bpermute_b32 v68, v198, v61
	s_waitcnt lgkmcnt(0)
	v_add_f32_e32 v61, v61, v68
	ds_bpermute_b32 v68, v199, v61
	v_mul_f32_e32 v42, v25, v75
	v_mul_f32_e32 v42, v57, v42
	s_waitcnt lgkmcnt(0)
	v_add_f32_e32 v57, v61, v68
	ds_bpermute_b32 v61, v200, v57
	s_waitcnt lgkmcnt(0)
	v_add_f32_e32 v57, v57, v61
	ds_bpermute_b32 v61, v201, v57
	v_rsq_f32_e32 v65, v65
	s_waitcnt lgkmcnt(0)
	v_add_f32_e32 v57, v57, v61
	ds_bpermute_b32 v61, v196, v57
	v_mul_f32_e32 v68, v18, v65
	v_mul_f32_e32 v33, v33, v68
	v_mul_f32_e32 v68, v17, v65
	v_mul_f32_e32 v31, v31, v68
	s_waitcnt lgkmcnt(0)
	v_add_f32_e32 v57, v57, v61
	v_fmamk_f32 v57, v57, 0x3c000000, v204
	v_mul_f32_e32 v68, v26, v65
	v_mul_f32_e32 v53, v53, v68
	v_mul_f32_e32 v65, v25, v65
	v_mul_f32_e32 v48, v48, v65
	v_mul_f32_e32 v68, v12, v12
	v_mul_f32_e32 v75, v34, v34
	v_fmac_f32_e32 v68, v14, v14
	v_fmac_f32_e32 v75, v38, v38
	v_add_f32_e32 v68, v68, v75
	ds_bpermute_b32 v75, v198, v68
	s_waitcnt lgkmcnt(0)
	v_add_f32_e32 v68, v68, v75
	ds_bpermute_b32 v75, v199, v68
	s_waitcnt lgkmcnt(0)
	v_add_f32_e32 v65, v68, v75
	ds_bpermute_b32 v68, v200, v65
	s_waitcnt lgkmcnt(0)
	v_add_f32_e32 v65, v65, v68
	ds_bpermute_b32 v68, v201, v65
	v_rsq_f32_e32 v57, v57
	s_waitcnt lgkmcnt(0)
	v_add_f32_e32 v65, v65, v68
	ds_bpermute_b32 v68, v196, v65
	v_mul_f32_e32 v61, v18, v57
	v_mul_f32_e32 v23, v23, v61
	v_mul_f32_e32 v61, v17, v57
	v_mul_f32_e32 v21, v21, v61
	s_waitcnt lgkmcnt(0)
	v_add_f32_e32 v65, v65, v68
	v_fmamk_f32 v65, v65, 0x3c000000, v204
	v_mul_f32_e32 v61, v26, v57
	v_mul_f32_e32 v45, v45, v61
	v_mul_f32_e32 v57, v25, v57
	v_mul_f32_e32 v41, v41, v57
	v_mul_f32_e32 v68, v10, v10
	v_mul_f32_e32 v75, v24, v24
	v_fmac_f32_e32 v68, v9, v9
	v_fmac_f32_e32 v75, v30, v30
	v_add_f32_e32 v68, v68, v75
	ds_bpermute_b32 v75, v198, v68
	s_waitcnt lgkmcnt(0)
	v_add_f32_e32 v68, v68, v75
	ds_bpermute_b32 v75, v199, v68
	s_waitcnt lgkmcnt(0)
	v_add_f32_e32 v57, v68, v75
	ds_bpermute_b32 v68, v200, v57
	s_waitcnt lgkmcnt(0)
	v_add_f32_e32 v57, v57, v68
	ds_bpermute_b32 v68, v201, v57
	v_rsq_f32_e32 v61, v65
	s_waitcnt lgkmcnt(0)
	v_add_f32_e32 v57, v57, v68
	ds_bpermute_b32 v68, v196, v57
	v_mul_f32_e32 v65, v18, v61
	v_mul_f32_e32 v14, v14, v65
	v_mul_f32_e32 v65, v17, v61
	v_mul_f32_e32 v12, v12, v65
	s_waitcnt lgkmcnt(0)
	v_add_f32_e32 v57, v57, v68
	v_fmamk_f32 v57, v57, 0x3c000000, v204
	v_mul_f32_e32 v65, v26, v61
	v_mul_f32_e32 v38, v38, v65
	v_mul_f32_e32 v61, v25, v61
	v_mul_f32_e32 v34, v34, v61
	v_mul_f32_e32 v68, v7, v7
	v_mul_f32_e32 v75, v19, v19
	v_fmac_f32_e32 v68, v8, v8
	v_fmac_f32_e32 v75, v16, v16
	v_add_f32_e32 v68, v68, v75
	ds_bpermute_b32 v75, v198, v68
	s_waitcnt lgkmcnt(0)
	v_add_f32_e32 v68, v68, v75
	ds_bpermute_b32 v75, v199, v68
	s_waitcnt lgkmcnt(0)
	v_add_f32_e32 v61, v68, v75
	ds_bpermute_b32 v68, v200, v61
	s_waitcnt lgkmcnt(0)
	v_add_f32_e32 v61, v61, v68
	ds_bpermute_b32 v68, v201, v61
	v_rsq_f32_e32 v57, v57
	s_waitcnt lgkmcnt(0)
	v_add_f32_e32 v61, v61, v68
	ds_bpermute_b32 v65, v196, v61
	v_mul_f32_e32 v68, v18, v57
	v_mul_f32_e32 v68, v9, v68
	v_mul_f32_e32 v9, v17, v57
	v_mul_f32_e32 v10, v10, v9
	s_waitcnt lgkmcnt(0)
	v_add_f32_e32 v9, v61, v65
	v_fmamk_f32 v9, v9, 0x3c000000, v204
	v_mul_f32_e32 v65, v26, v57
	v_mul_f32_e32 v65, v30, v65
	v_mul_f32_e32 v30, v25, v57
	v_mul_f32_e32 v79, v24, v30
	v_mul_f32_e32 v61, v6, v6
	v_fmac_f32_e32 v61, v5, v5
	v_mul_f32_e32 v75, v15, v15
	v_fmac_f32_e32 v75, v13, v13
	v_add_f32_e32 v61, v61, v75
	ds_bpermute_b32 v75, v198, v61
	s_waitcnt lgkmcnt(0)
	v_add_f32_e32 v57, v61, v75
	ds_bpermute_b32 v61, v199, v57
	s_waitcnt lgkmcnt(0)
	v_add_f32_e32 v24, v57, v61
	ds_bpermute_b32 v30, v200, v24
	s_waitcnt lgkmcnt(0)
	v_add_f32_e32 v24, v24, v30
	ds_bpermute_b32 v30, v201, v24
	s_waitcnt lgkmcnt(0)
	v_add_f32_e32 v24, v24, v30
	ds_bpermute_b32 v30, v196, v24
	v_rsq_f32_e32 v9, v9
	s_nop 0
	v_mul_f32_e32 v57, v18, v9
	v_mul_f32_e32 v57, v8, v57
	s_waitcnt lgkmcnt(0)
	v_add_f32_e32 v8, v24, v30
	v_fmamk_f32 v8, v8, 0x3c000000, v204
	v_add3_u32 v78, s10, v4, v3
	v_cvt_pk_bf16_f32 v3, v27, s0
	ds_write_b16 v78, v3
	v_cvt_pk_bf16_f32 v3, v28, s0
	ds_write_b16 v78, v3 offset:64
	v_cvt_pk_bf16_f32 v3, v35, s0
	ds_write_b16 v78, v3 offset:128
	v_cvt_pk_bf16_f32 v3, v36, s0
	ds_write_b16 v78, v3 offset:192
	v_cvt_pk_bf16_f32 v3, v43, s0
	ds_write_b16 v78, v3 offset:256
	v_cvt_pk_bf16_f32 v3, v44, s0
	ds_write_b16 v78, v3 offset:320
	v_cvt_pk_bf16_f32 v3, v51, s0
	ds_write_b16 v78, v3 offset:384
	v_cvt_pk_bf16_f32 v3, v52, s0
	ds_write_b16 v78, v3 offset:448
	v_cvt_pk_bf16_f32 v3, v59, s0
	ds_write_b16 v78, v3 offset:1024
	v_cvt_pk_bf16_f32 v3, v60, s0
	ds_write_b16 v78, v3 offset:1088
	v_cvt_pk_bf16_f32 v3, v66, s0
	ds_write_b16 v78, v3 offset:1152
	v_cvt_pk_bf16_f32 v3, v67, s0
	ds_write_b16 v78, v3 offset:1216
	v_cvt_pk_bf16_f32 v3, v70, s0
	ds_write_b16 v78, v3 offset:1280
	v_cvt_pk_bf16_f32 v3, v71, s0
	ds_write_b16 v78, v3 offset:1344
	v_cvt_pk_bf16_f32 v3, v73, s0
	ds_write_b16 v78, v3 offset:1408
	v_cvt_pk_bf16_f32 v3, v74, s0
	ds_write_b16 v78, v3 offset:1472
	v_cvt_pk_bf16_f32 v3, v69, s0
	ds_write_b16 v78, v3 offset:2048
	v_cvt_pk_bf16_f32 v3, v72, s0
	v_mul_f32_e32 v30, v17, v9
	ds_write_b16 v78, v3 offset:2112
	v_cvt_pk_bf16_f32 v3, v76, s0
	v_mul_f32_e32 v7, v7, v30
	v_mul_f32_e32 v30, v26, v9
	v_mul_f32_e32 v9, v25, v9
	ds_write_b16 v78, v3 offset:2176
	v_cvt_pk_bf16_f32 v3, v77, s0
	v_mul_f32_e32 v75, v19, v9
	ds_write_b16 v78, v3 offset:2240
	v_cvt_pk_bf16_f32 v3, v33, s0
	ds_write_b16 v78, v3 offset:2304
	v_cvt_pk_bf16_f32 v3, v31, s0
	ds_write_b16 v78, v3 offset:2368
	v_cvt_pk_bf16_f32 v3, v23, s0
	v_mul_f32_e32 v16, v16, v30
	ds_write_b16 v78, v3 offset:2432
	v_cvt_pk_bf16_f32 v3, v21, s0
	ds_write_b16 v78, v3 offset:2496
	v_cvt_pk_bf16_f32 v3, v14, s0
	ds_write_b16 v78, v3 offset:3072
	v_cvt_pk_bf16_f32 v3, v12, s0
	ds_write_b16 v78, v3 offset:3136
	v_cvt_pk_bf16_f32 v3, v68, s0
	v_rsq_f32_e32 v8, v8
	ds_write_b16 v78, v3 offset:3200
	v_cvt_pk_bf16_f32 v3, v10, s0
	v_mul_f32_e32 v9, v18, v8
	ds_write_b16 v78, v3 offset:3264
	v_cvt_pk_bf16_f32 v3, v57, s0
	v_mul_f32_e32 v18, v5, v9
	v_mul_f32_e32 v5, v17, v8
	ds_write_b16 v78, v3 offset:3328
	v_cvt_pk_bf16_f32 v3, v7, s0
	v_mul_f32_e32 v6, v6, v5
	ds_write_b16 v78, v3 offset:3392
	v_cvt_pk_bf16_f32 v3, v18, s0
	v_mul_f32_e32 v5, v26, v8
	s_add_u32 s4, s8, s64
	ds_write_b16 v78, v3 offset:3456
	v_cvt_pk_bf16_f32 v3, v6, s0
	v_mul_f32_e32 v17, v13, v5
	v_mul_f32_e32 v5, v25, v8
	s_addc_u32 s5, s9, s65
	ds_write_b16 v78, v3 offset:3520
	v_mul_f32_e32 v61, v15, v5
	v_lshl_add_u64 v[4:5], s[4:5], 0, v[188:189]
	s_mov_b64 s[4:5], 0x18800000
	v_lshl_add_u32 v80, v1, 7, v2
	s_waitcnt lgkmcnt(0)
	v_lshl_add_u64 v[8:9], v[4:5], 0, s[4:5]
	ds_read_b128 v[4:7], v80
	v_or_b32_e32 v3, 8, v1
	v_lshlrev_b32_e32 v12, 11, v1
	v_mov_b32_e32 v13, v146
	v_lshl_add_u32 v10, v3, 7, v2
	v_lshl_add_u64 v[18:19], v[8:9], 0, v[12:13]
	ds_read_b128 v[12:15], v10
	s_waitcnt lgkmcnt(1)
	global_store_dwordx4 v[18:19], v[4:7], off
	s_mov_b64 s[6:7], 0
	s_nop 0
	v_lshlrev_b32_e32 v4, 11, v3
	v_mov_b32_e32 v5, v146
	v_or_b32_e32 v3, 16, v1
	v_lshl_add_u64 v[24:25], v[8:9], 0, v[4:5]
	v_lshl_add_u32 v21, v3, 7, v2
	v_or_b32_e32 v1, 24, v1
	ds_read_b128 v[4:7], v21
	s_waitcnt lgkmcnt(1)
	global_store_dwordx4 v[24:25], v[12:15], off
	v_lshl_add_u32 v23, v1, 7, v2
	v_lshlrev_b32_e32 v2, 11, v1
	v_lshlrev_b32_e32 v12, 11, v3
	v_mov_b32_e32 v13, v146
	v_lshl_add_u64 v[26:27], v[8:9], 0, v[12:13]
	ds_read_b128 v[12:15], v23
	v_mov_b32_e32 v3, v146
	v_lshl_add_u64 v[30:31], v[8:9], 0, v[2:3]
	s_waitcnt lgkmcnt(1)
	global_store_dwordx4 v[26:27], v[4:7], off
	v_cvt_pk_bf16_f32 v1, v11, s0
	s_waitcnt lgkmcnt(0)
	global_store_dwordx4 v[30:31], v[12:15], off
	s_waitcnt lgkmcnt(0)
	ds_write_b16 v78, v1
	v_cvt_pk_bf16_f32 v1, v20, s0
	ds_write_b16 v78, v1 offset:64
	v_cvt_pk_bf16_f32 v1, v22, s0
	ds_write_b16 v78, v1 offset:128
	v_cvt_pk_bf16_f32 v1, v29, s0
	ds_write_b16 v78, v1 offset:192
	v_cvt_pk_bf16_f32 v1, v32, s0
	ds_write_b16 v78, v1 offset:256
	v_cvt_pk_bf16_f32 v1, v37, s0
	ds_write_b16 v78, v1 offset:320
	v_cvt_pk_bf16_f32 v1, v40, s0
	ds_write_b16 v78, v1 offset:384
	v_cvt_pk_bf16_f32 v1, v46, s0
	ds_write_b16 v78, v1 offset:448
	v_cvt_pk_bf16_f32 v1, v49, s0
	ds_write_b16 v78, v1 offset:1024
	v_cvt_pk_bf16_f32 v1, v55, s0
	ds_write_b16 v78, v1 offset:1088
	v_cvt_pk_bf16_f32 v1, v58, s0
	ds_write_b16 v78, v1 offset:1152
	v_cvt_pk_bf16_f32 v1, v63, s0
	ds_write_b16 v78, v1 offset:1216
	v_cvt_pk_bf16_f32 v1, v62, s0
	ds_write_b16 v78, v1 offset:1280
	v_cvt_pk_bf16_f32 v1, v64, s0
	ds_write_b16 v78, v1 offset:1344
	v_cvt_pk_bf16_f32 v1, v54, s0
	ds_write_b16 v78, v1 offset:1408
	v_cvt_pk_bf16_f32 v1, v56, s0
	ds_write_b16 v78, v1 offset:1472
	v_cvt_pk_bf16_f32 v1, v47, s0
	ds_write_b16 v78, v1 offset:2048
	v_cvt_pk_bf16_f32 v1, v50, s0
	ds_write_b16 v78, v1 offset:2112
	v_cvt_pk_bf16_f32 v1, v39, s0
	ds_write_b16 v78, v1 offset:2176
	v_cvt_pk_bf16_f32 v1, v42, s0
	ds_write_b16 v78, v1 offset:2240
	v_cvt_pk_bf16_f32 v1, v53, s0
	ds_write_b16 v78, v1 offset:2304
	v_cvt_pk_bf16_f32 v1, v48, s0
	ds_write_b16 v78, v1 offset:2368
	v_cvt_pk_bf16_f32 v1, v45, s0
	ds_write_b16 v78, v1 offset:2432
	v_cvt_pk_bf16_f32 v1, v41, s0
	ds_write_b16 v78, v1 offset:2496
	v_cvt_pk_bf16_f32 v1, v38, s0
	ds_write_b16 v78, v1 offset:3072
	v_cvt_pk_bf16_f32 v1, v34, s0
	ds_write_b16 v78, v1 offset:3136
	v_cvt_pk_bf16_f32 v1, v65, s0
	ds_write_b16 v78, v1 offset:3200
	v_cvt_pk_bf16_f32 v1, v79, s0
	ds_write_b16 v78, v1 offset:3264
	v_cvt_pk_bf16_f32 v1, v16, s0
	ds_write_b16 v78, v1 offset:3328
	v_cvt_pk_bf16_f32 v1, v75, s0
	ds_write_b16 v78, v1 offset:3392
	v_cvt_pk_bf16_f32 v1, v17, s0
	ds_write_b16 v78, v1 offset:3456
	v_cvt_pk_bf16_f32 v1, v61, s0
	ds_write_b16 v78, v1 offset:3520
	s_waitcnt lgkmcnt(0)
	ds_read_b128 v[2:5], v80
	ds_read_b128 v[6:9], v10
	ds_read_b128 v[10:13], v21
	ds_read_b128 v[14:17], v23
	s_waitcnt lgkmcnt(3)
	global_store_dwordx4 v[18:19], v[2:5], off offset:128
	s_waitcnt lgkmcnt(2)
	global_store_dwordx4 v[24:25], v[6:9], off offset:128
	s_waitcnt lgkmcnt(1)
	global_store_dwordx4 v[26:27], v[10:13], off offset:128
	s_waitcnt lgkmcnt(0)
	global_store_dwordx4 v[30:31], v[14:17], off offset:128
	s_waitcnt lgkmcnt(0)
	s_waitcnt lgkmcnt(0)
	s_barrier
